# new software-pipelined static GQA attention loop (LDS prefetch one stage ahead); flat->global loads in attention
# speedup vs baseline: 1.0036x; 1.0036x over previous
; template <int DQK, bool STATIC>
; DI void attn_item8(const bf16_t* __restrict__ Q, const bf16_t* __restrict__ Kp, const bf16_t* __restrict__ Vt, int nkeys, char* lds,
;                   const bf16_t* __restrict__ Pg, bf16_t* __restrict__ Yg  , float mfix) {
;     ...
;   for (int ks = 0; ks < NQS; ++ks) qf[ks] = *(const bf16x8*)(Q + (size_t)(32 * w + l31) * DQK + 16 * ks + 8 * h);
;   f32x16 o[2];
; #pragma unroll
;   for (int d = 0; d < 2; ++d)
; #pragma unroll
;     for (int e = 0; e < 16; ++e) o[d][e] = 0.f;
;   float m_run = STATIC ? mfix : -1e30f, l_run = 0.f;
;   u32x4 rk[NKC], rv[1];
;   int koffg[NKC], koffl[NKC];
; #pragma unroll
;   for (int i = 0; i < NKC; ++i) { const int c = tid + 512 * i; const int key = c / KCH, part = c % KCH; koffg[i] = (c < 64 * KCH) ? c * 8 : 0; koffl[i] = (c < 64 * KCH) ? key * KSTR + part * 16 : -1; }
;   const int vdv0 = tid >> 3, vpart = tid & 7;
;   const bf16_t* vg = Vt + (size_t)vdv0 * T + vpart * 8;
;   const int voffl = KBUF + vdv0 * VSTR + vpart * 16;
;   const int nt = nkeys >> 6;
; #pragma unroll
; DI void phase_mix(KP p, int l, char* lds) {
;     ...
;       const bool isA = (it < 64) || (it >= 128 && it < 136);
;       int b, hd, q0, k0, nk;
;       if (it < 128) { const int i2 = it & 63; b = 2 * xcd + (i2 >> 5); hd = (i2 >> 3) & 3; q0 = (i2 & 7) * 256; k0 = 0; nk = T; }
;       else { const int i2 = (it - 128) & 7; b = 2 * xcd + (i2 >> 2); hd = i2 & 3; q0 = SEQ; k0 = SEQ; nk = CL; }
;       const size_t r0 = (size_t)b * T + q0; const size_t bh = (size_t)b * 4 + hd, bk = (size_t)b * 2 + (hd >> 1);
;       if (isA) {
;         if (sbA <= 30.f) attn_item8<96, true>(QA + (bh * T + q0) * 96, KA + (bh * T + k0) * 96, VAT + bh * 64 * T + k0, nk, lds, P + r0 * NIN + O_GA + 64 * hd, Y + r0 * 1024 + 64 * hd, sbA);
;         else attn_item8<96, false>(QA + (bh * T + q0) * 96, KA + (bh * T + k0) * 96, VAT + bh * 64 * T + k0, nk, lds, P + r0 * NIN + O_GA + 64 * hd, Y + r0 * 1024 + 64 * hd, 0.f);
;       } else {
;         if (sbB <= 30.f) attn_item8<64, true>(QB + (bh * T + q0) * 64, KB + (bk * T + k0) * 64, VBT + bk * 64 * T + k0, nk, lds, P + r0 * NIN + O_GB + 64 * hd, Y + r0 * 1024 + 256 + 64 * hd, sbB);
;         else attn_item8<64, false>(QB + (bh * T + q0) * 64, KB + (bk * T + k0) * 64, VBT + bk * 64 * T + k0, nk, lds, P + r0 * NIN + O_GB + 64 * hd, Y + r0 * 1024 + 256 + 64 * hd, 0.f);
.LBB0_37:
	s_cmp_gt_u32 s64, 63
	s_cselect_b64 s[20:21], -1, 0
	s_and_b32 s2, s64, 0x7ffffff8
	s_cmpk_lg_i32 s2, 0x80
	s_cselect_b64 s[34:35], -1, 0
	s_and_b32 s2, s18, 1
	v_readlane_b32 s18, v253, 5
	s_or_b32 s2, s2, s18
	s_mul_i32 s18, s2, 0x900
	s_and_b64 s[36:37], s[20:21], s[34:35]
	s_and_b32 s34, s19, 3
	s_add_u32 s20, s18, s4
	s_lshl_b32 s18, s2, 2
	s_or_b32 s35, s18, s34
	s_mul_i32 s69, s35, 0x900
	s_add_u32 s56, s69, s4
	s_addc_u32 s57, 0, s5
	s_mov_b64 s[4:5], -1
	s_and_b64 vcc, exec, s[36:37]
	s_mul_i32 s14, s20, 0x14c0
	s_cbranch_vccz .LBB0_75
	s_lshl_b32 s2, s2, 1
	s_lshr_b32 s4, s34, 1
	s_or_b32 s2, s2, s4
	s_lshl_b64 s[4:5], s[56:57], 7
	v_readlane_b32 s18, v255, 44
	s_add_u32 s76, s18, s4
	v_readlane_b32 s4, v255, 45
	s_addc_u32 s77, s4, s5
	s_mul_i32 s4, s2, 0x900
	s_add_u32 s4, s4, s48
	s_addc_u32 s5, 0, s49
	s_lshl_b64 s[4:5], s[4:5], 7
	v_readlane_b32 s18, v255, 47
	s_add_u32 s54, s18, s4
	v_readlane_b32 s4, v255, 48
	s_addc_u32 s55, s4, s5
	s_mul_i32 s2, s2, 0x48000
	v_readlane_b32 s4, v255, 49
	s_add_u32 s2, s4, s2
	v_readlane_b32 s4, v255, 50
	s_addc_u32 s4, s4, 0
	s_lshl_b32 s5, s48, 1
	s_add_u32 s50, s2, s5
	s_addc_u32 s51, s4, 0
	s_add_u32 s2, s42, s14
	s_addc_u32 s4, s43, 0
	s_lshl_b32 s5, s34, 7
	s_add_u32 s2, s2, s5
	s_addc_u32 s4, s4, 0
	s_add_u32 s36, s2, 0x8c0
	s_addc_u32 s37, s4, 0
	s_lshl_b32 s2, s20, 11
	v_readlane_b32 s4, v255, 31
	s_add_u32 s2, s4, s2
	v_readlane_b32 s4, v255, 32
	s_addc_u32 s4, s4, 0
	s_add_u32 s2, s2, s5
	s_addc_u32 s4, s4, 0
	s_add_u32 s40, s2, 0x200
	s_addc_u32 s41, s4, 0
	s_mov_b64 s[4:5], exec
	v_readlane_b32 s18, v255, 51
	v_readlane_b32 s19, v255, 52
	s_and_b64 s[18:19], s[4:5], s[18:19]
	s_xor_b64 s[4:5], s[18:19], s[4:5]
	s_mov_b64 exec, s[18:19]
	s_cbranch_execz .LBB0_54
	v_mov_b32_e32 v40, v196
	s_movk_i32 s2, 0xffe0
	v_ashrrev_i32_e32 v0, 1, v40
	v_bfi_b32 v188, s2, v0, v40
	v_ashrrev_i32_e32 v189, 31, v188
	v_bfe_u32 v187, v40, 5, 1
	v_lshlrev_b64 v[34:35], 7, v[188:189]
	v_lshl_add_u64 v[34:35], s[76:77], 0, v[34:35]
	v_lshlrev_b32_e32 v0, 4, v187
	v_lshl_add_u64 v[34:35], v[34:35], 0, v[0:1]
	v_ashrrev_i32_e32 v42, 3, v40
	v_and_b32_e32 v43, 7, v40
	v_mov_b64_e32 v[36:37], s[50:51]
	s_movk_i32 s2, 0x1200
	global_load_dwordx4 v[98:101], v[34:35], off offset:32
	global_load_dwordx4 v[102:105], v[34:35], off offset:64
	global_load_dwordx4 v[106:109], v[34:35], off offset:96
	v_mad_i64_i32 v[36:37], s[18:19], v42, s2, v[36:37]
	v_lshlrev_b32_e32 v38, 4, v43
	v_mov_b32_e32 v39, v1
	v_lshl_add_u64 v[122:123], v[36:37], 0, v[38:39]
	global_load_dwordx4 v[110:113], v[34:35], off
	s_nop 0
	global_load_dwordx4 v[34:37], v[122:123], off
	v_ashrrev_i32_e32 v38, 31, v40
	v_lshrrev_b32_e32 v38, 29, v38
	v_add_u32_e32 v38, v40, v38
	v_lshrrev_b32_e32 v39, 3, v38
	s_movk_i32 s2, 0x200
	v_lshlrev_b32_e32 v38, 3, v40
	v_cmp_gt_i32_e32 vcc, s2, v40
	v_add_lshl_u32 v39, v39, v40, 4
	s_nop 0
	v_cndmask_b32_e32 v38, 0, v38, vcc
	v_cndmask_b32_e32 v126, -1, v39, vcc
	v_cmp_lt_i32_e64 s[44:45], -1, v126
	v_cmp_gt_i32_e32 vcc, 0, v126
	v_ashrrev_i32_e32 v39, 31, v38
	s_and_saveexec_b64 s[18:19], vcc
	s_xor_b64 s[18:19], exec, s[18:19]
	s_or_saveexec_b64 s[18:19], s[18:19]
	v_add_u32_e32 v41, 0, v126
	s_xor_b64 exec, exec, s[18:19]
	s_cbranch_execz .LBB0_41
	v_lshl_add_u64 v[44:45], v[38:39], 1, s[54:55]
	global_load_dwordx4 v[44:47], v[44:45], off
	s_waitcnt vmcnt(0) lgkmcnt(0)
	ds_write_b128 v41, v[44:47]
.LBB0_41:
	s_or_b64 exec, exec, s[18:19]
	s_movk_i32 s2, 0x88
	v_mul_lo_u32 v42, v42, s2
	v_lshl_add_u32 v127, v43, 4, v42
	v_add_u32_e32 v42, 0, v127
	v_add_u32_e32 v43, 0x2400, v42
	v_lshl_add_u64 v[124:125], v[38:39], 1, s[54:55]
	s_waitcnt vmcnt(0) lgkmcnt(0)
	ds_write2_b64 v43, v[34:35], v[36:37] offset1:1
	v_add_co_u32_e32 v34, vcc, 0x2000, v124
	s_nop 1
	v_addc_co_u32_e32 v35, vcc, 0, v125, vcc
	global_load_dwordx4 v[114:117], v[34:35], off
	global_load_dwordx4 v[118:121], v[122:123], off offset:128
	s_and_saveexec_b64 s[18:19], s[44:45]
	s_cbranch_execz .LBB0_43
	s_waitcnt vmcnt(0) lgkmcnt(0)
	ds_write_b128 v41, v[114:117] offset:17920

; template <int DQK, bool STATIC>
; DI void attn_item8(const bf16_t* __restrict__ Q, const bf16_t* __restrict__ Kp, const bf16_t* __restrict__ Vt, int nkeys, char* lds,
;                   const bf16_t* __restrict__ Pg, bf16_t* __restrict__ Yg  , float mfix) {
;     ...
;     f32x16 s0, s1;
;     bf16x8 kf[2][NQS];
; #pragma unroll
;     for (int kb = 0; kb < 2; ++kb)
; #pragma unroll
;       for (int ks = 0; ks < NQS; ++ks) kf[kb][ks] = *(const bf16x8*)(cur + (32 * kb + l31) * KSTR + (2 * ks + h) * 16);
;     u32x4 vw[2][2][2];
; #pragma unroll
;     for (int kb = 0; kb < 2; ++kb)
; #pragma unroll
;       for (int s2 = 0; s2 < 2; ++s2)
; #pragma unroll
;         for (int d = 0; d < 2; ++d) {
;           const char* vp = cur + KBUF + (32 * d + l31) * VSTR + (32 * kb + 16 * s2 + 4 * h) * 2;
;           u32x2 v0 = *(const u32x2*)vp, v1 = *(const u32x2*)(vp + 16);
;           u32x4 t4 = {v0.x, v0.y, v1.x, v1.y}; vw[kb][s2][d] = t4;
;         }
; #pragma unroll
;     for (int e = 0; e < 16; ++e) { s0[e] = STATIC ? -mfix : 0.f; s1[e] = STATIC ? -mfix : 0.f; }
; #pragma unroll
;     for (int ks = 0; ks < NQS; ++ks) s0 = MFMA32(kf[0][ks], qf[ks], s0);
;     if (!STATIC) {
;       float mx = s0[0];
; #pragma unroll
;       for (int e = 1; e < 16; ++e) mx = fmaxf(mx, s0[e]);
;       mx = fmaxf(mx, __shfl_xor(mx, 32));
;       if (!__all(mx <= m_run + 8.f)) {
;         const float m_new = fmaxf(m_run, mx);
;         const float alpha = __builtin_amdgcn_exp2f(m_run - m_new);
;         m_run = m_new; l_run *= alpha;
; #pragma unroll
;         for (int d = 0; d < 2; ++d)
; #pragma unroll
;           for (int e = 0; e < 16; ++e) o[d][e] *= alpha;
;       }
;     }
; #pragma unroll
;     for (int ks = 0; ks < NQS; ++ks) s1 = MFMA32(kf[1][ks], qf[ks], s1);
;     {
;       float ps = 0.f;
; #pragma unroll
;       for (int e = 0; e < 16; ++e) { float p = STATIC ? __builtin_amdgcn_exp2f(s0[e]) : __builtin_amdgcn_exp2f(s0[e] - m_run); s0[e] = p; ps += p; }
;       l_run += ps;
;     }
;     ...
;     for (int s2 = 0; s2 < 2; ++s2) {
;       u32x4 pw = {cvtpk(s0[8 * s2], s0[8 * s2 + 1]), cvtpk(s0[8 * s2 + 2], s0[8 * s2 + 3]), cvtpk(s0[8 * s2 + 4], s0[8 * s2 + 5]), cvtpk(s0[8 * s2 + 6], s0[8 * s2 + 7])};
;       bf16x8 pf = __builtin_bit_cast(bf16x8, pw);
; #pragma unroll
;       for (int d = 0; d < 2; ++d) o[d] = MFMA32(__builtin_bit_cast(bf16x8, vw[0][s2][d]), pf, o[d]);
;     }
;     {
.LBB0_45:
	s_and_b32 s18, s49, 1
	s_mul_i32 s21, s18, 0x8c00
	s_xor_b32 s18, s18, 1
	s_mul_i32 s19, s18, 0x8c00
	s_add_i32 s49, s49, 1
	s_cmp_eq_u32 s49, 1
	s_cbranch_scc1 .Lab_nodef
	v_add_f32_e32 v137, v66, v68
	v_add_f32_e32 v138, v67, v69
	v_add_f32_e32 v137, v70, v137
	v_add_f32_e32 v138, v71, v138
	v_add_f32_e32 v137, v72, v137
	v_add_f32_e32 v138, v73, v138
	v_add_f32_e32 v137, v74, v137
	v_add_f32_e32 v138, v75, v138
	v_add_f32_e32 v137, v76, v137
	v_add_f32_e32 v138, v77, v138
	v_add_f32_e32 v137, v78, v137
	v_add_f32_e32 v138, v79, v138
	v_add_f32_e32 v137, v80, v137
	v_add_f32_e32 v138, v81, v138
	v_add_f32_e32 v137, v137, v138
	v_add_f32_e32 v215, v215, v137
.Lab_nodef:
	s_cmp_lt_u32 s49, s65
	s_cbranch_scc0 .Lab_noload
	s_lshl_b32 s52, s49, 14
	s_mov_b32 s53, 0
	v_lshl_add_u64 v[140:141], v[124:125], 0, s[52:53]
	global_load_dwordx4 v[114:117], v[140:141], off
	s_add_u32 s52, s52, 0x2000
	v_lshl_add_u64 v[140:141], v[124:125], 0, s[52:53]
	global_load_dwordx4 v[162:165], v[140:141], off
	s_lshl_b32 s52, s49, 8
	v_lshl_add_u64 v[140:141], v[122:123], 0, s[52:53]
	global_load_dwordx4 v[118:121], v[140:141], off
	global_load_dwordx4 v[166:169], v[140:141], off offset:128
.Lab_noload:
	s_add_i32 s18, s21, 0x4600
	v_add3_u32 v131, s21, v0, v129
	v_add3_u32 v133, s21, v128, v130
	v_add_u32_e32 v135, 0x3000, v133
	v_add_u32_e32 v133, 0x2000, v133
	v_add3_u32 v132, s18, v0, v129
	v_add3_u32 v134, s18, v128, v130
	v_add_u32_e32 v136, 0x3000, v134
	v_add_u32_e32 v134, 0x2000, v134
	ds_read_b128 v[216:219], v131 offset:0
	ds_read_b128 v[220:223], v131 offset:32
	ds_read_b128 v[224:227], v131 offset:64
	ds_read_b128 v[228:231], v131 offset:96
	ds_read_b128 v[232:235], v131 offset:4608
	ds_read_b128 v[236:239], v131 offset:4640
	ds_read_b128 v[240:243], v131 offset:4672
	ds_read_b128 v[244:247], v131 offset:4704
	s_waitcnt lgkmcnt(4)
	v_mfma_f32_32x32x16_bf16 v[82:97], v[216:219], v[110:113], v[2:17]
	v_mfma_f32_32x32x16_bf16 v[82:97], v[220:223], v[98:101], v[82:97]
	v_mfma_f32_32x32x16_bf16 v[82:97], v[224:227], v[102:105], v[82:97]
	v_mfma_f32_32x32x16_bf16 v[82:97], v[228:231], v[106:109], v[82:97]
	s_waitcnt lgkmcnt(0)
	ds_read2_b64 v[216:219], v133 offset0:128 offset1:130
	ds_read2_b64 v[220:223], v135 offset0:160 offset1:162
	ds_read2_b64 v[224:227], v133 offset0:132 offset1:134
	ds_read2_b64 v[228:231], v135 offset0:164 offset1:166
	v_mfma_f32_32x32x16_bf16 v[66:81], v[232:235], v[110:113], v[2:17]
	s_nop 5
	v_exp_f32_e32 v82, v82
	v_exp_f32_e32 v83, v83
	v_exp_f32_e32 v84, v84
	v_exp_f32_e32 v85, v85
	v_mfma_f32_32x32x16_bf16 v[66:81], v[236:239], v[98:101], v[66:81]
	v_exp_f32_e32 v86, v86
	v_exp_f32_e32 v87, v87
	v_exp_f32_e32 v88, v88
	v_exp_f32_e32 v89, v89
	v_mfma_f32_32x32x16_bf16 v[66:81], v[240:243], v[102:105], v[66:81]
	v_exp_f32_e32 v90, v90
	v_exp_f32_e32 v91, v91
	v_exp_f32_e32 v92, v92
	v_exp_f32_e32 v93, v93
	v_mfma_f32_32x32x16_bf16 v[66:81], v[244:247], v[106:109], v[66:81]
	v_exp_f32_e32 v94, v94
	v_exp_f32_e32 v95, v95
	v_exp_f32_e32 v96, v96
	v_exp_f32_e32 v97, v97
	v_cvt_pk_bf16_f32 v146, v82, v83
	v_cvt_pk_bf16_f32 v147, v84, v85
	v_cvt_pk_bf16_f32 v148, v86, v87
	v_cvt_pk_bf16_f32 v149, v88, v89
	v_cvt_pk_bf16_f32 v150, v90, v91
	v_cvt_pk_bf16_f32 v151, v92, v93
	v_cvt_pk_bf16_f32 v152, v94, v95
	v_cvt_pk_bf16_f32 v153, v96, v97
	s_waitcnt lgkmcnt(0)
	ds_read2_b64 v[232:235], v133 offset0:136 offset1:138
	ds_read2_b64 v[236:239], v135 offset0:168 offset1:170
	ds_read2_b64 v[240:243], v133 offset0:140 offset1:142
	ds_read2_b64 v[244:247], v135 offset0:172 offset1:174
	v_mfma_f32_32x32x16_bf16 v[50:65], v[216:219], v[146:149], v[50:65]
	v_exp_f32_e32 v66, v66
	v_exp_f32_e32 v67, v67
	v_exp_f32_e32 v68, v68
	v_exp_f32_e32 v69, v69
	v_mfma_f32_32x32x16_bf16 v[34:49], v[220:223], v[146:149], v[34:49]
	v_exp_f32_e32 v70, v70
	v_exp_f32_e32 v71, v71
	v_exp_f32_e32 v72, v72
	v_exp_f32_e32 v73, v73
	v_mfma_f32_32x32x16_bf16 v[50:65], v[224:227], v[150:153], v[50:65]
	v_exp_f32_e32 v74, v74
	v_exp_f32_e32 v75, v75
	v_exp_f32_e32 v76, v76
	v_exp_f32_e32 v77, v77
	v_mfma_f32_32x32x16_bf16 v[34:49], v[228:231], v[150:153], v[34:49]
	v_exp_f32_e32 v78, v78
	v_exp_f32_e32 v79, v79
	v_exp_f32_e32 v80, v80
	v_exp_f32_e32 v81, v81
	v_cvt_pk_bf16_f32 v146, v66, v67
	v_cvt_pk_bf16_f32 v147, v68, v69
	v_cvt_pk_bf16_f32 v148, v70, v71
	v_cvt_pk_bf16_f32 v149, v72, v73
	v_cvt_pk_bf16_f32 v150, v74, v75
	v_cvt_pk_bf16_f32 v151, v76, v77
	v_cvt_pk_bf16_f32 v152, v78, v79
	v_cvt_pk_bf16_f32 v153, v80, v81
	s_waitcnt lgkmcnt(0)
	ds_read_b128 v[216:219], v132 offset:0
	ds_read_b128 v[220:223], v132 offset:32
	ds_read_b128 v[224:227], v132 offset:64
	ds_read_b128 v[228:231], v132 offset:96
	v_mfma_f32_32x32x16_bf16 v[50:65], v[232:235], v[146:149], v[50:65]
	v_add_f32_e32 v137, v82, v84
	v_add_f32_e32 v138, v83, v85
	v_add_f32_e32 v137, v86, v137
	v_add_f32_e32 v138, v87, v138
	v_mfma_f32_32x32x16_bf16 v[34:49], v[236:239], v[146:149], v[34:49]
	v_add_f32_e32 v137, v88, v137
	v_add_f32_e32 v138, v89, v138
	v_add_f32_e32 v137, v90, v137
	v_add_f32_e32 v138, v91, v138
	v_mfma_f32_32x32x16_bf16 v[50:65], v[240:243], v[150:153], v[50:65]
	v_add_f32_e32 v137, v92, v137
	v_add_f32_e32 v138, v93, v138
	v_add_f32_e32 v137, v94, v137
	v_add_f32_e32 v138, v95, v138
	v_mfma_f32_32x32x16_bf16 v[34:49], v[244:247], v[150:153], v[34:49]
	v_add_f32_e32 v137, v96, v137
	v_add_f32_e32 v138, v97, v138
	v_add_f32_e32 v137, v137, v138
	v_add_f32_e32 v215, v215, v137
	s_cmp_lt_u32 s49, s65
	s_cbranch_scc0 .Lab_nostage0
	s_waitcnt vmcnt(1)
	s_add_i32 s52, s19, 0x0
	v_add_u32_e32 v139, s52, v127
	v_add_u32_e32 v139, 0x2400, v139
	ds_write2_b64 v139, v[118:119], v[120:121] offset1:1
	s_and_saveexec_b64 vcc, s[44:45]
	v_add_u32_e32 v139, s52, v126
	ds_write_b128 v139, v[114:117]
	s_or_b64 exec, exec, vcc
; template <int DQK, bool STATIC>
; DI void attn_item8(const bf16_t* __restrict__ Q, const bf16_t* __restrict__ Kp, const bf16_t* __restrict__ Vt, int nkeys, char* lds,
;                   const bf16_t* __restrict__ Pg, bf16_t* __restrict__ Yg  , float mfix) {
;     ...
;     bf16x8 kf[2][NQS];
; #pragma unroll
;     for (int kb = 0; kb < 2; ++kb)
; #pragma unroll
;       for (int ks = 0; ks < NQS; ++ks) kf[kb][ks] = *(const bf16x8*)(cur + (32 * kb + l31) * KSTR + (2 * ks + h) * 16);
;     u32x4 vw[2][2][2];
; #pragma unroll
;     for (int kb = 0; kb < 2; ++kb)
; #pragma unroll
;       for (int s2 = 0; s2 < 2; ++s2)
; #pragma unroll
;         for (int d = 0; d < 2; ++d) {
;           const char* vp = cur + KBUF + (32 * d + l31) * VSTR + (32 * kb + 16 * s2 + 4 * h) * 2;
;           u32x2 v0 = *(const u32x2*)vp, v1 = *(const u32x2*)(vp + 16);
;           u32x4 t4 = {v0.x, v0.y, v1.x, v1.y}; vw[kb][s2][d] = t4;
;         }
; #pragma unroll
;     for (int e = 0; e < 16; ++e) { s0[e] = STATIC ? -mfix : 0.f; s1[e] = STATIC ? -mfix : 0.f; }
; #pragma unroll
;     for (int ks = 0; ks < NQS; ++ks) s0 = MFMA32(kf[0][ks], qf[ks], s0);
;     if (!STATIC) {
;       float mx = s0[0];
; #pragma unroll
;       for (int e = 1; e < 16; ++e) mx = fmaxf(mx, s0[e]);
;       mx = fmaxf(mx, __shfl_xor(mx, 32));
;       if (!__all(mx <= m_run + 8.f)) {
;         const float m_new = fmaxf(m_run, mx);
;         const float alpha = __builtin_amdgcn_exp2f(m_run - m_new);
;         m_run = m_new; l_run *= alpha;
; #pragma unroll
;         for (int d = 0; d < 2; ++d)
; #pragma unroll
;           for (int e = 0; e < 16; ++e) o[d][e] *= alpha;
;       }
;     }
; #pragma unroll
;     for (int ks = 0; ks < NQS; ++ks) s1 = MFMA32(kf[1][ks], qf[ks], s1);
;     {
;       float ps = 0.f;
; #pragma unroll
;       for (int e = 0; e < 16; ++e) { float p = STATIC ? __builtin_amdgcn_exp2f(s0[e]) : __builtin_amdgcn_exp2f(s0[e] - m_run); s0[e] = p; ps += p; }
;       l_run += ps;
;     ...
;     for (int s2 = 0; s2 < 2; ++s2) {
;       u32x4 pw = {cvtpk(s0[8 * s2], s0[8 * s2 + 1]), cvtpk(s0[8 * s2 + 2], s0[8 * s2 + 3]), cvtpk(s0[8 * s2 + 4], s0[8 * s2 + 5]), cvtpk(s0[8 * s2 + 6], s0[8 * s2 + 7])};
;       bf16x8 pf = __builtin_bit_cast(bf16x8, pw);
; #pragma unroll
;       for (int d = 0; d < 2; ++d) o[d] = MFMA32(__builtin_bit_cast(bf16x8, vw[0][s2][d]), pf, o[d]);
;     }
;     {
;       float ps = 0.f;
.Lab_nostage0:
	ds_read_b128 v[232:235], v132 offset:4608
	ds_read_b128 v[236:239], v132 offset:4640
	ds_read_b128 v[240:243], v132 offset:4672
	ds_read_b128 v[244:247], v132 offset:4704
	s_waitcnt lgkmcnt(4)
	v_mfma_f32_32x32x16_bf16 v[82:97], v[216:219], v[110:113], v[2:17]
	v_add_f32_e32 v137, v66, v68
	v_add_f32_e32 v138, v67, v69
	v_add_f32_e32 v137, v70, v137
	v_mfma_f32_32x32x16_bf16 v[82:97], v[220:223], v[98:101], v[82:97]
	v_add_f32_e32 v138, v71, v138
	v_add_f32_e32 v137, v72, v137
	v_add_f32_e32 v138, v73, v138
	v_mfma_f32_32x32x16_bf16 v[82:97], v[224:227], v[102:105], v[82:97]
	v_add_f32_e32 v137, v74, v137
	v_add_f32_e32 v138, v75, v138
	v_add_f32_e32 v137, v76, v137
	v_mfma_f32_32x32x16_bf16 v[82:97], v[228:231], v[106:109], v[82:97]
	v_add_f32_e32 v138, v77, v138
	v_add_f32_e32 v137, v78, v137
	v_add_f32_e32 v138, v79, v138
	v_add_f32_e32 v137, v80, v137
	v_add_f32_e32 v138, v81, v138
	v_add_f32_e32 v137, v137, v138
	v_add_f32_e32 v215, v215, v137
	s_waitcnt lgkmcnt(0)
	ds_read2_b64 v[216:219], v134 offset0:128 offset1:130
	ds_read2_b64 v[220:223], v136 offset0:160 offset1:162
	ds_read2_b64 v[224:227], v134 offset0:132 offset1:134
	ds_read2_b64 v[228:231], v136 offset0:164 offset1:166
	v_mfma_f32_32x32x16_bf16 v[66:81], v[232:235], v[110:113], v[2:17]
	v_exp_f32_e32 v82, v82
	v_exp_f32_e32 v83, v83
	v_exp_f32_e32 v84, v84
	v_exp_f32_e32 v85, v85
	v_mfma_f32_32x32x16_bf16 v[66:81], v[236:239], v[98:101], v[66:81]
	v_exp_f32_e32 v86, v86
	v_exp_f32_e32 v87, v87
	v_exp_f32_e32 v88, v88
	v_exp_f32_e32 v89, v89
	v_mfma_f32_32x32x16_bf16 v[66:81], v[240:243], v[102:105], v[66:81]
	v_exp_f32_e32 v90, v90
	v_exp_f32_e32 v91, v91
	v_exp_f32_e32 v92, v92
	v_exp_f32_e32 v93, v93
	v_mfma_f32_32x32x16_bf16 v[66:81], v[244:247], v[106:109], v[66:81]
	v_exp_f32_e32 v94, v94
	v_exp_f32_e32 v95, v95
	v_exp_f32_e32 v96, v96
	v_exp_f32_e32 v97, v97
	v_cvt_pk_bf16_f32 v146, v82, v83
	v_cvt_pk_bf16_f32 v147, v84, v85
	v_cvt_pk_bf16_f32 v148, v86, v87
	v_cvt_pk_bf16_f32 v149, v88, v89
	v_cvt_pk_bf16_f32 v150, v90, v91
	v_cvt_pk_bf16_f32 v151, v92, v93
	v_cvt_pk_bf16_f32 v152, v94, v95
	v_cvt_pk_bf16_f32 v153, v96, v97
	s_waitcnt lgkmcnt(0)
	ds_read2_b64 v[232:235], v134 offset0:136 offset1:138
	ds_read2_b64 v[236:239], v136 offset0:168 offset1:170
	ds_read2_b64 v[240:243], v134 offset0:140 offset1:142
	ds_read2_b64 v[244:247], v136 offset0:172 offset1:174
	v_mfma_f32_32x32x16_bf16 v[50:65], v[216:219], v[146:149], v[50:65]
	v_exp_f32_e32 v66, v66
	v_exp_f32_e32 v67, v67
	v_exp_f32_e32 v68, v68
	v_exp_f32_e32 v69, v69
	v_mfma_f32_32x32x16_bf16 v[34:49], v[220:223], v[146:149], v[34:49]
	v_exp_f32_e32 v70, v70
	v_exp_f32_e32 v71, v71
	v_exp_f32_e32 v72, v72
	v_exp_f32_e32 v73, v73
	v_mfma_f32_32x32x16_bf16 v[50:65], v[224:227], v[150:153], v[50:65]
	v_exp_f32_e32 v74, v74
	v_exp_f32_e32 v75, v75
	v_exp_f32_e32 v76, v76
	v_exp_f32_e32 v77, v77
	v_mfma_f32_32x32x16_bf16 v[34:49], v[228:231], v[150:153], v[34:49]
	v_exp_f32_e32 v78, v78
	v_exp_f32_e32 v79, v79
	v_exp_f32_e32 v80, v80
	v_exp_f32_e32 v81, v81
	v_cvt_pk_bf16_f32 v146, v66, v67
	v_cvt_pk_bf16_f32 v147, v68, v69
	v_cvt_pk_bf16_f32 v148, v70, v71
	v_cvt_pk_bf16_f32 v149, v72, v73
	v_cvt_pk_bf16_f32 v150, v74, v75
	v_cvt_pk_bf16_f32 v151, v76, v77
	v_cvt_pk_bf16_f32 v152, v78, v79
	v_cvt_pk_bf16_f32 v153, v80, v81
	s_waitcnt lgkmcnt(0)
	v_mfma_f32_32x32x16_bf16 v[50:65], v[232:235], v[146:149], v[50:65]
	v_add_f32_e32 v137, v82, v84
	v_add_f32_e32 v138, v83, v85
	v_add_f32_e32 v137, v86, v137
	v_add_f32_e32 v138, v87, v138
	v_mfma_f32_32x32x16_bf16 v[34:49], v[236:239], v[146:149], v[34:49]
	v_add_f32_e32 v137, v88, v137
	v_add_f32_e32 v138, v89, v138
	v_add_f32_e32 v137, v90, v137
	v_add_f32_e32 v138, v91, v138
	v_mfma_f32_32x32x16_bf16 v[50:65], v[240:243], v[150:153], v[50:65]
	v_add_f32_e32 v137, v92, v137
	v_add_f32_e32 v138, v93, v138
	v_add_f32_e32 v137, v94, v137
	v_add_f32_e32 v138, v95, v138
	v_mfma_f32_32x32x16_bf16 v[34:49], v[244:247], v[150:153], v[34:49]
	v_add_f32_e32 v137, v96, v137
	v_add_f32_e32 v138, v97, v138
	v_add_f32_e32 v137, v137, v138
	v_add_f32_e32 v215, v215, v137
	s_cmp_lt_u32 s49, s65
	s_cbranch_scc0 .Lab_nostage1
	s_waitcnt vmcnt(0)
	s_add_i32 s52, s19, 0x4600
	v_add_u32_e32 v139, s52, v127
	v_add_u32_e32 v139, 0x2400, v139
	ds_write2_b64 v139, v[166:167], v[168:169] offset1:1
	s_and_saveexec_b64 vcc, s[44:45]
	v_add_u32_e32 v139, s52, v126
	ds_write_b128 v139, v[162:165]
	s_or_b64 exec, exec, vcc
.Lab_nostage1:
.Lab_pairend:
	s_cmp_eq_u32 s49, s65
	s_waitcnt lgkmcnt(0)
	s_barrier
	s_cbranch_scc0 .LBB0_45
	v_add_f32_e32 v137, v66, v68
	v_add_f32_e32 v138, v67, v69
	v_add_f32_e32 v137, v70, v137
	v_add_f32_e32 v138, v71, v138
	v_add_f32_e32 v137, v72, v137
	v_add_f32_e32 v138, v73, v138
	v_add_f32_e32 v137, v74, v137
	v_add_f32_e32 v138, v75, v138
	v_add_f32_e32 v137, v76, v137
	v_add_f32_e32 v138, v77, v138
	v_add_f32_e32 v137, v78, v137
	v_add_f32_e32 v138, v79, v138
	v_add_f32_e32 v137, v80, v137
	v_add_f32_e32 v138, v81, v138
	v_add_f32_e32 v137, v137, v138
	v_add_f32_e32 v215, v215, v137
	s_nop 7

; template <int DQK, bool STATIC>
; DI void attn_item8(const bf16_t* __restrict__ Q, const bf16_t* __restrict__ Kp, const bf16_t* __restrict__ Vt, int nkeys, char* lds,
;                   const bf16_t* __restrict__ Pg, bf16_t* __restrict__ Yg  , float mfix) {
;     ...
;   for (int ks = 0; ks < NQS; ++ks) qf[ks] = *(const bf16x8*)(Q + (size_t)(32 * w + l31) * DQK + 16 * ks + 8 * h);
;   f32x16 o[2];
; #pragma unroll
;   for (int d = 0; d < 2; ++d)
; #pragma unroll
;     for (int e = 0; e < 16; ++e) o[d][e] = 0.f;
;   float m_run = STATIC ? mfix : -1e30f, l_run = 0.f;
;   u32x4 rk[NKC], rv[1];
;   int koffg[NKC], koffl[NKC];
; #pragma unroll
;   for (int i = 0; i < NKC; ++i) { const int c = tid + 512 * i; const int key = c / KCH, part = c % KCH; koffg[i] = (c < 64 * KCH) ? c * 8 : 0; koffl[i] = (c < 64 * KCH) ? key * KSTR + part * 16 : -1; }
;   const int vdv0 = tid >> 3, vpart = tid & 7;
;   const bf16_t* vg = Vt + (size_t)vdv0 * T + vpart * 8;
;   const int voffl = KBUF + vdv0 * VSTR + vpart * 16;
;   const int nt = nkeys >> 6;
; #pragma unroll
;   for (int i = 0; i < NKC; ++i) rk[i] = *(const u32x4*)(Kp + koffg[i]);
; #pragma unroll
;   for (int i = 0; i < 1; ++i) rv[i] = *(const u32x4*)(vg + (size_t)i * 32 * T);
; #pragma unroll
;   for (int i = 0; i < NKC; ++i) if (koffl[i] >= 0) *(u32x4*)(lds + koffl[i]) = rk[i];
; #pragma unroll
;   for (int i = 0; i < 1; ++i) { u32x2 a = {rv[i].x, rv[i].y}, b = {rv[i].z, rv[i].w}; *(u32x2*)(lds + voffl + i * 32 * VSTR) = a; *(u32x2*)(lds + voffl + i * 32 * VSTR + 8) = b; }
;   {
; #pragma unroll
;     for (int i = 0; i < NKC; ++i) rk[i] = *(const u32x4*)(Kp + (size_t)64 * DQK + koffg[i]);
;     rv[0] = *(const u32x4*)(vg + 64);
; #pragma unroll
;     for (int i = 0; i < NKC; ++i) if (koffl[i] >= 0) *(u32x4*)(lds + BUF + koffl[i]) = rk[i];
;     { u32x2 a = {rv[0].x, rv[0].y}, b = {rv[0].z, rv[0].w}; *(u32x2*)(lds + BUF + voffl) = a; *(u32x2*)(lds + BUF + voffl + 8) = b; }
; DI void phase_mix(KP p, int l, char* lds) {
;     ...
;         else attn_item8<64, false>(QB + (bh * T + q0) * 64, KB + (bk * T + k0) * 64, VBT + bk * 64 * T + k0, nk, lds, P + r0 * NIN + O_GB + 64 * hd, Y + r0 * 1024 + 256 + 64 * hd, 0.f);
.LBB0_54:
	s_andn2_saveexec_b64 s[4:5], s[4:5]
	s_cbranch_execz .LBB0_74
	v_mov_b32_e32 v40, v196
	s_movk_i32 s2, 0xffe0
	s_waitcnt lgkmcnt(0)
	v_ashrrev_i32_e32 v0, 1, v40
	v_bfi_b32 v188, s2, v0, v40
	v_ashrrev_i32_e32 v189, 31, v188
	v_bfe_u32 v187, v40, 5, 1
	v_lshlrev_b64 v[34:35], 7, v[188:189]
	v_lshl_add_u64 v[34:35], s[76:77], 0, v[34:35]
	v_lshlrev_b32_e32 v0, 4, v187
	v_lshl_add_u64 v[34:35], v[34:35], 0, v[0:1]
	v_ashrrev_i32_e32 v42, 3, v40
	v_and_b32_e32 v43, 7, v40
	v_mov_b64_e32 v[36:37], s[50:51]
	s_movk_i32 s2, 0x1200
	global_load_dwordx4 v[98:101], v[34:35], off offset:32
	global_load_dwordx4 v[102:105], v[34:35], off offset:64
	global_load_dwordx4 v[106:109], v[34:35], off offset:96
	v_mad_i64_i32 v[36:37], s[18:19], v42, s2, v[36:37]
	v_lshlrev_b32_e32 v38, 4, v43
	v_mov_b32_e32 v39, v1
	v_lshl_add_u64 v[166:167], v[36:37], 0, v[38:39]
	global_load_dwordx4 v[110:113], v[34:35], off
	s_nop 0
	global_load_dwordx4 v[34:37], v[166:167], off
	v_ashrrev_i32_e32 v38, 31, v40
	v_lshrrev_b32_e32 v38, 29, v38
	v_add_u32_e32 v38, v40, v38
	v_lshrrev_b32_e32 v39, 3, v38
	s_movk_i32 s2, 0x200
	v_lshlrev_b32_e32 v38, 3, v40
	v_cmp_gt_i32_e32 vcc, s2, v40
	v_add_lshl_u32 v39, v39, v40, 4
	s_nop 0
	v_cndmask_b32_e32 v38, 0, v38, vcc
	v_cndmask_b32_e32 v170, -1, v39, vcc
	v_cmp_lt_i32_e64 s[44:45], -1, v170
	v_cmp_gt_i32_e32 vcc, 0, v170
	v_ashrrev_i32_e32 v39, 31, v38
	s_and_saveexec_b64 s[18:19], vcc
	s_xor_b64 s[18:19], exec, s[18:19]
	s_or_saveexec_b64 s[18:19], s[18:19]
	v_add_u32_e32 v41, 0, v170
	s_xor_b64 exec, exec, s[18:19]
	s_cbranch_execz .LBB0_57
	v_lshl_add_u64 v[44:45], v[38:39], 1, s[54:55]
	global_load_dwordx4 v[44:47], v[44:45], off
	s_waitcnt vmcnt(0) lgkmcnt(0)
	ds_write_b128 v41, v[44:47]
.LBB0_57:
	s_or_b64 exec, exec, s[18:19]
	s_movk_i32 s2, 0x88
	v_mul_lo_u32 v42, v42, s2
	v_lshl_add_u32 v171, v43, 4, v42
	v_add_u32_e32 v42, 0, v171
	v_add_u32_e32 v43, 0x2400, v42
	v_lshl_add_u64 v[168:169], v[38:39], 1, s[54:55]
	s_waitcnt vmcnt(0) lgkmcnt(0)
	ds_write2_b64 v43, v[34:35], v[36:37] offset1:1
	v_add_co_u32_e32 v34, vcc, 0x2000, v168
	s_nop 1
	v_addc_co_u32_e32 v35, vcc, 0, v169, vcc
	global_load_dwordx4 v[114:117], v[34:35], off
	global_load_dwordx4 v[118:121], v[166:167], off offset:128
	s_and_saveexec_b64 s[18:19], s[44:45]
	s_cbranch_execz .LBB0_59
	s_waitcnt vmcnt(0) lgkmcnt(0)
	ds_write_b128 v41, v[114:117] offset:17920

; template <int DQK, bool STATIC>
; DI void attn_item8(const bf16_t* __restrict__ Q, const bf16_t* __restrict__ Kp, const bf16_t* __restrict__ Vt, int nkeys, char* lds,
;                   const bf16_t* __restrict__ Pg, bf16_t* __restrict__ Yg  , float mfix) {
;     ...
;     if (more) {
; #pragma unroll
;       for (int i = 0; i < NKC; ++i) rk[i] = *(const u32x4*)(Kp + (size_t)(j + 1) * 64 * DQK + koffg[i]);
; #pragma unroll
;       for (int i = 0; i < 1; ++i) rv[i] = *(const u32x4*)(vg + (size_t)i * 32 * T + (j + 1) * 64);
;     }
.LBB0_64:
	v_cndmask_b32_e64 v66, 0, 1, s[50:51]
	v_cmp_ne_u32_e64 s[46:47], 1, v66
	s_andn2_b64 vcc, exec, s[50:51]
	s_cbranch_vccnz .LBB0_66
	s_or_b32 s19, s18, s52
	s_add_i32 s2, s19, 2
	s_lshl_b64 s[72:73], s[2:3], 13
	v_lshl_add_u64 v[66:67], v[168:169], 0, s[72:73]
	s_lshl_b32 s72, s19, 6
	s_ashr_i32 s73, s72, 31
	v_lshl_add_u64 v[68:69], s[72:73], 1, v[166:167]
	s_waitcnt vmcnt(0)
	global_load_dwordx4 v[114:117], v[66:67], off
	global_load_dwordx4 v[118:121], v[68:69], off offset:256
	s_mov_b64 s[72:73], 0x1000

; template <int DQK, bool STATIC>
; DI void attn_item8(const bf16_t* __restrict__ Q, const bf16_t* __restrict__ Kp, const bf16_t* __restrict__ Vt, int nkeys, char* lds,
;                   const bf16_t* __restrict__ Pg, bf16_t* __restrict__ Yg  , float mfix) {
;     ...
;   for (int ks = 0; ks < NQS; ++ks) qf[ks] = *(const bf16x8*)(Q + (size_t)(32 * w + l31) * DQK + 16 * ks + 8 * h);
;   f32x16 o[2];
; #pragma unroll
;   for (int d = 0; d < 2; ++d)
; #pragma unroll
;     for (int e = 0; e < 16; ++e) o[d][e] = 0.f;
;   float m_run = STATIC ? mfix : -1e30f, l_run = 0.f;
;   u32x4 rk[NKC], rv[1];
;   int koffg[NKC], koffl[NKC];
; #pragma unroll
;   for (int i = 0; i < NKC; ++i) { const int c = tid + 512 * i; const int key = c / KCH, part = c % KCH; koffg[i] = (c < 64 * KCH) ? c * 8 : 0; koffl[i] = (c < 64 * KCH) ? key * KSTR + part * 16 : -1; }
;   const int vdv0 = tid >> 3, vpart = tid & 7;
;   const bf16_t* vg = Vt + (size_t)vdv0 * T + vpart * 8;
;   const int voffl = KBUF + vdv0 * VSTR + vpart * 16;
;   const int nt = nkeys >> 6;
; #pragma unroll
;   for (int i = 0; i < NKC; ++i) rk[i] = *(const u32x4*)(Kp + koffg[i]);
; #pragma unroll
;   for (int i = 0; i < 1; ++i) rv[i] = *(const u32x4*)(vg + (size_t)i * 32 * T);
; #pragma unroll
;   for (int i = 0; i < NKC; ++i) if (koffl[i] >= 0) *(u32x4*)(lds + koffl[i]) = rk[i];
; DI void phase_mix(KP p, int l, char* lds) {
;     ...
;       const bool isA = (it < 64) || (it >= 128 && it < 136);
;       int b, hd, q0, k0, nk;
;       if (it < 128) { const int i2 = it & 63; b = 2 * xcd + (i2 >> 5); hd = (i2 >> 3) & 3; q0 = (i2 & 7) * 256; k0 = 0; nk = T; }
;       else { const int i2 = (it - 128) & 7; b = 2 * xcd + (i2 >> 2); hd = i2 & 3; q0 = SEQ; k0 = SEQ; nk = CL; }
;       const size_t r0 = (size_t)b * T + q0; const size_t bh = (size_t)b * 4 + hd, bk = (size_t)b * 2 + (hd >> 1);
;       if (isA) {
;         if (sbA <= 30.f) attn_item8<96, true>(QA + (bh * T + q0) * 96, KA + (bh * T + k0) * 96, VAT + bh * 64 * T + k0, nk, lds, P + r0 * NIN + O_GA + 64 * hd, Y + r0 * 1024 + 64 * hd, sbA);
.LBB0_75:
	s_andn2_b64 vcc, exec, s[4:5]
	s_cbranch_vccnz .LBB0_31
	s_mul_i32 s2, s57, 0xc0
	s_mul_hi_u32 s4, s56, 0xc0
	s_add_i32 s4, s4, s2
	s_mul_i32 s2, s56, 0xc0
	v_readlane_b32 s5, v255, 38
	s_add_u32 s50, s5, s2
	v_readlane_b32 s2, v255, 39
	s_addc_u32 s51, s2, s4
	s_add_i32 s2, s69, s48
	s_mulk_i32 s2, 0xc0
	v_readlane_b32 s4, v255, 40
	s_add_u32 s56, s4, s2
	v_readlane_b32 s2, v255, 41
	s_addc_u32 s57, s2, 0
	s_mul_i32 s35, s35, 0x48000
	v_readlane_b32 s2, v255, 42
	s_add_u32 s2, s2, s35
	v_readlane_b32 s4, v255, 43
	s_addc_u32 s4, s4, 0
	s_lshl_b32 s5, s48, 1
	s_add_u32 s54, s2, s5
	s_addc_u32 s55, s4, 0
	s_add_u32 s2, s42, s14
	s_addc_u32 s4, s43, 0
	s_lshl_b32 s5, s34, 7
	s_add_u32 s2, s2, s5
	s_addc_u32 s4, s4, 0
	s_add_u32 s36, s2, 0x2c0
	s_addc_u32 s37, s4, 0
	s_lshl_b32 s2, s20, 11
	v_readlane_b32 s4, v255, 31
	s_add_u32 s2, s4, s2
	v_readlane_b32 s4, v255, 32
	s_addc_u32 s4, s4, 0
	s_add_u32 s40, s2, s5
	s_addc_u32 s41, s4, 0
	s_mov_b64 s[4:5], exec
	v_readlane_b32 s18, v255, 53
	v_readlane_b32 s19, v255, 54
	s_and_b64 s[18:19], s[4:5], s[18:19]
	s_xor_b64 s[4:5], s[18:19], s[4:5]
	s_mov_b64 exec, s[18:19]
	s_cbranch_execz .LBB0_98
	v_mov_b32_e32 v42, v196
	s_movk_i32 s2, 0xffe0
	s_waitcnt lgkmcnt(0)
	v_ashrrev_i32_e32 v0, 1, v42
	v_bfe_u32 v187, v42, 5, 1
	v_bfi_b32 v188, s2, v0, v42
	v_mov_b64_e32 v[34:35], s[50:51]
	s_movk_i32 s2, 0xc0
	v_mad_i64_i32 v[34:35], s[18:19], v188, s2, v[34:35]
	v_lshlrev_b32_e32 v0, 4, v187
	v_add_u32_e32 v44, 0x200, v42
	s_movk_i32 s2, 0x100
	v_lshl_add_u64 v[38:39], v[34:35], 0, v[0:1]
	v_lshlrev_b32_e32 v34, 3, v44
	v_cmp_gt_i32_e32 vcc, s2, v42
	global_load_dwordx4 v[98:101], v[38:39], off offset:32
	global_load_dwordx4 v[102:105], v[38:39], off offset:64
	global_load_dwordx4 v[106:109], v[38:39], off offset:96
	global_load_dwordx4 v[110:113], v[38:39], off offset:128
	v_cndmask_b32_e32 v134, 0, v34, vcc
	v_ashrrev_i32_e32 v45, 3, v42
	v_and_b32_e32 v46, 7, v42
	v_ashrrev_i32_e32 v135, 31, v134
	v_mov_b64_e32 v[40:41], s[54:55]
	s_movk_i32 s2, 0x1200
	v_lshl_add_u64 v[34:35], v[134:135], 1, s[56:57]
	v_mad_i64_i32 v[40:41], s[18:19], v45, s2, v[40:41]
	v_lshlrev_b32_e32 v48, 4, v46
	v_mov_b32_e32 v49, v1
	s_waitcnt vmcnt(0)
	global_load_dwordx4 v[114:117], v[38:39], off offset:160
	s_nop 0
	global_load_dwordx4 v[34:37], v[34:35], off
	v_lshl_add_u64 v[136:137], v[40:41], 0, v[48:49]
	global_load_dwordx4 v[118:121], v[38:39], off
	s_nop 0
	global_load_dwordx4 v[38:41], v[136:137], off
	s_mov_b32 s2, 0x2aaaaaab
	v_mul_hi_i32 v43, v42, s2
	v_lshrrev_b32_e32 v47, 31, v43
	v_lshrrev_b32_e32 v43, 1, v43
	v_add_u32_e32 v43, v43, v47
	v_lshlrev_b32_e32 v47, 3, v42
	v_cmp_gt_i32_e64 s[44:45], s58, v42
	v_add_lshl_u32 v43, v43, v42, 4
	s_nop 0
	v_cndmask_b32_e64 v138, 0, v47, s[44:45]
	v_cndmask_b32_e64 v140, -1, v43, s[44:45]
	v_ashrrev_i32_e32 v139, 31, v138
	v_cmp_lt_i32_e64 s[44:45], -1, v140
	v_add_u32_e32 v43, 0, v140
	s_and_saveexec_b64 s[18:19], s[44:45]
	s_cbranch_execz .LBB0_79
	v_lshl_add_u64 v[48:49], v[138:139], 1, s[56:57]
	global_load_dwordx4 v[48:51], v[48:49], off
	s_waitcnt vmcnt(0) lgkmcnt(0)
	ds_write_b128 v43, v[48:51]

; template <int DQK, bool STATIC>
; DI void attn_item8(const bf16_t* __restrict__ Q, const bf16_t* __restrict__ Kp, const bf16_t* __restrict__ Vt, int nkeys, char* lds,
;                   const bf16_t* __restrict__ Pg, bf16_t* __restrict__ Yg  , float mfix) {
;     ...
;   for (int i = 0; i < NKC; ++i) if (koffl[i] >= 0) *(u32x4*)(lds + koffl[i]) = rk[i];
; #pragma unroll
;   for (int i = 0; i < 1; ++i) { u32x2 a = {rv[i].x, rv[i].y}, b = {rv[i].z, rv[i].w}; *(u32x2*)(lds + voffl + i * 32 * VSTR) = a; *(u32x2*)(lds + voffl + i * 32 * VSTR + 8) = b; }
;   {
; #pragma unroll
;     for (int i = 0; i < NKC; ++i) rk[i] = *(const u32x4*)(Kp + (size_t)64 * DQK + koffg[i]);
;     rv[0] = *(const u32x4*)(vg + 64);
; #pragma unroll
;     for (int i = 0; i < NKC; ++i) if (koffl[i] >= 0) *(u32x4*)(lds + BUF + koffl[i]) = rk[i];
;     { u32x2 a = {rv[0].x, rv[0].y}, b = {rv[0].z, rv[0].w}; *(u32x2*)(lds + BUF + voffl) = a; *(u32x2*)(lds + BUF + voffl + 8) = b; }
.LBB0_81:
	s_or_b64 exec, exec, s[18:19]
	s_movk_i32 s2, 0x88
	s_waitcnt vmcnt(0) lgkmcnt(0)
	v_mul_lo_u32 v34, v45, s2
	v_lshl_add_u32 v142, v46, 4, v34
	s_add_u32 s18, s56, 0x3000
	v_add_u32_e32 v34, 0, v142
	s_addc_u32 s19, s57, 0
	v_add_u32_e32 v35, 0x3400, v34
	v_lshl_add_u64 v[36:37], v[138:139], 1, s[18:19]
	ds_write2_b64 v35, v[38:39], v[40:41] offset1:1
	global_load_dwordx4 v[122:125], v[36:37], off
	v_lshl_add_u64 v[36:37], v[134:135], 1, s[18:19]
	global_load_dwordx4 v[126:129], v[36:37], off
	global_load_dwordx4 v[130:133], v[136:137], off offset:128
	s_and_saveexec_b64 s[18:19], s[44:45]
	s_cbranch_execz .LBB0_83
	s_waitcnt vmcnt(0) lgkmcnt(0)
	ds_write_b128 v43, v[122:125] offset:22016

; template <int DQK, bool STATIC>
; DI void attn_item8(const bf16_t* __restrict__ Q, const bf16_t* __restrict__ Kp, const bf16_t* __restrict__ Vt, int nkeys, char* lds,
;                   const bf16_t* __restrict__ Pg, bf16_t* __restrict__ Yg  , float mfix) {
;     ...
;     if (more) {
; #pragma unroll
;       for (int i = 0; i < NKC; ++i) rk[i] = *(const u32x4*)(Kp + (size_t)(j + 1) * 64 * DQK + koffg[i]);
; #pragma unroll
;       for (int i = 0; i < 1; ++i) rv[i] = *(const u32x4*)(vg + (size_t)i * 32 * T + (j + 1) * 64);
;     }
.LBB0_90:
	v_cndmask_b32_e64 v66, 0, 1, s[76:77]
	v_cmp_ne_u32_e64 s[48:49], 1, v66
	s_andn2_b64 vcc, exec, s[76:77]
	s_cbranch_vccnz .LBB0_92
	s_or_b32 s19, s18, s20
	s_add_i32 s35, s19, 2
	s_mul_hi_u32 s53, s35, 0x3000
	s_mulk_i32 s35, 0x3000
	s_add_u32 s52, s56, s35
	s_addc_u32 s53, s57, s53
	v_lshl_add_u64 v[66:67], v[138:139], 1, s[52:53]
	v_lshl_add_u64 v[68:69], v[134:135], 1, s[52:53]
	s_lshl_b32 s52, s19, 6
	s_ashr_i32 s53, s52, 31
	s_waitcnt vmcnt(0)
	global_load_dwordx4 v[122:125], v[66:67], off
	global_load_dwordx4 v[126:129], v[68:69], off
	v_lshl_add_u64 v[66:67], s[52:53], 1, v[136:137]
	global_load_dwordx4 v[130:133], v[66:67], off offset:256

; template <int DQK, bool STATIC>
; DI void attn_item8(const bf16_t* __restrict__ Q, const bf16_t* __restrict__ Kp, const bf16_t* __restrict__ Vt, int nkeys, char* lds,
;                   const bf16_t* __restrict__ Pg, bf16_t* __restrict__ Yg  , float mfix) {
;     ...
;   for (int ks = 0; ks < NQS; ++ks) qf[ks] = *(const bf16x8*)(Q + (size_t)(32 * w + l31) * DQK + 16 * ks + 8 * h);
;   f32x16 o[2];
; #pragma unroll
;   for (int d = 0; d < 2; ++d)
; #pragma unroll
;     for (int e = 0; e < 16; ++e) o[d][e] = 0.f;
;   float m_run = STATIC ? mfix : -1e30f, l_run = 0.f;
;   u32x4 rk[NKC], rv[1];
;   int koffg[NKC], koffl[NKC];
; #pragma unroll
;   for (int i = 0; i < NKC; ++i) { const int c = tid + 512 * i; const int key = c / KCH, part = c % KCH; koffg[i] = (c < 64 * KCH) ? c * 8 : 0; koffl[i] = (c < 64 * KCH) ? key * KSTR + part * 16 : -1; }
;   const int vdv0 = tid >> 3, vpart = tid & 7;
;   const bf16_t* vg = Vt + (size_t)vdv0 * T + vpart * 8;
;   const int voffl = KBUF + vdv0 * VSTR + vpart * 16;
;   const int nt = nkeys >> 6;
; #pragma unroll
;   for (int i = 0; i < NKC; ++i) rk[i] = *(const u32x4*)(Kp + koffg[i]);
; #pragma unroll
;   for (int i = 0; i < 1; ++i) rv[i] = *(const u32x4*)(vg + (size_t)i * 32 * T);
; #pragma unroll
;   for (int i = 0; i < NKC; ++i) if (koffl[i] >= 0) *(u32x4*)(lds + koffl[i]) = rk[i];
; DI void phase_mix(KP p, int l, char* lds) {
;     ...
;         else attn_item8<96, false>(QA + (bh * T + q0) * 96, KA + (bh * T + k0) * 96, VAT + bh * 64 * T + k0, nk, lds, P + r0 * NIN + O_GA + 64 * hd, Y + r0 * 1024 + 64 * hd, 0.f);
.LBB0_98:
	s_andn2_saveexec_b64 s[4:5], s[4:5]
	s_cbranch_execz .LBB0_30
	v_mov_b32_e32 v42, v196
	s_movk_i32 s2, 0xffe0
	s_waitcnt lgkmcnt(0)
	v_ashrrev_i32_e32 v0, 1, v42
	v_bfe_u32 v187, v42, 5, 1
	v_bfi_b32 v188, s2, v0, v42
	v_mov_b64_e32 v[34:35], s[50:51]
	s_movk_i32 s2, 0xc0
	v_mad_i64_i32 v[34:35], s[18:19], v188, s2, v[34:35]
	v_lshlrev_b32_e32 v0, 4, v187
	v_add_u32_e32 v44, 0x200, v42
	s_movk_i32 s2, 0x100
	v_lshl_add_u64 v[38:39], v[34:35], 0, v[0:1]
	v_lshlrev_b32_e32 v34, 3, v44
	v_cmp_gt_i32_e32 vcc, s2, v42
	global_load_dwordx4 v[98:101], v[38:39], off offset:32
	global_load_dwordx4 v[102:105], v[38:39], off offset:64
	global_load_dwordx4 v[106:109], v[38:39], off offset:96
	global_load_dwordx4 v[110:113], v[38:39], off offset:128
	v_cndmask_b32_e32 v190, 0, v34, vcc
	v_ashrrev_i32_e32 v45, 3, v42
	v_and_b32_e32 v46, 7, v42
	v_ashrrev_i32_e32 v191, 31, v190
	v_mov_b64_e32 v[40:41], s[54:55]
	s_movk_i32 s2, 0x1200
	v_lshl_add_u64 v[34:35], v[190:191], 1, s[56:57]
	v_mad_i64_i32 v[40:41], s[18:19], v45, s2, v[40:41]
	v_lshlrev_b32_e32 v48, 4, v46
	v_mov_b32_e32 v49, v1
	s_waitcnt vmcnt(0)
	global_load_dwordx4 v[114:117], v[38:39], off offset:160
	s_nop 0
	global_load_dwordx4 v[34:37], v[34:35], off
	v_lshl_add_u64 v[192:193], v[40:41], 0, v[48:49]
	global_load_dwordx4 v[118:121], v[38:39], off
	s_nop 0
	global_load_dwordx4 v[38:41], v[192:193], off
	s_mov_b32 s2, 0x2aaaaaab
	v_mul_hi_i32 v43, v42, s2
	v_lshrrev_b32_e32 v47, 31, v43
	v_lshrrev_b32_e32 v43, 1, v43
	v_add_u32_e32 v43, v43, v47
	v_lshlrev_b32_e32 v47, 3, v42
	v_cmp_gt_i32_e64 s[44:45], s58, v42
	v_add_lshl_u32 v43, v43, v42, 4
	s_nop 0
	v_cndmask_b32_e64 v194, 0, v47, s[44:45]
	v_cndmask_b32_e64 v216, -1, v43, s[44:45]
	v_ashrrev_i32_e32 v195, 31, v194
	v_cmp_lt_i32_e64 s[44:45], -1, v216
	v_add_u32_e32 v43, 0, v216
	s_and_saveexec_b64 s[18:19], s[44:45]
	s_cbranch_execz .LBB0_101
	v_lshl_add_u64 v[48:49], v[194:195], 1, s[56:57]
	global_load_dwordx4 v[48:51], v[48:49], off
	s_waitcnt vmcnt(0) lgkmcnt(0)
	ds_write_b128 v43, v[48:51]

; template <int DQK, bool STATIC>
; DI void attn_item8(const bf16_t* __restrict__ Q, const bf16_t* __restrict__ Kp, const bf16_t* __restrict__ Vt, int nkeys, char* lds,
;                   const bf16_t* __restrict__ Pg, bf16_t* __restrict__ Yg  , float mfix) {
;     ...
;   for (int i = 0; i < NKC; ++i) if (koffl[i] >= 0) *(u32x4*)(lds + koffl[i]) = rk[i];
; #pragma unroll
;   for (int i = 0; i < 1; ++i) { u32x2 a = {rv[i].x, rv[i].y}, b = {rv[i].z, rv[i].w}; *(u32x2*)(lds + voffl + i * 32 * VSTR) = a; *(u32x2*)(lds + voffl + i * 32 * VSTR + 8) = b; }
;   {
; #pragma unroll
;     for (int i = 0; i < NKC; ++i) rk[i] = *(const u32x4*)(Kp + (size_t)64 * DQK + koffg[i]);
;     rv[0] = *(const u32x4*)(vg + 64);
; #pragma unroll
;     for (int i = 0; i < NKC; ++i) if (koffl[i] >= 0) *(u32x4*)(lds + BUF + koffl[i]) = rk[i];
;     { u32x2 a = {rv[0].x, rv[0].y}, b = {rv[0].z, rv[0].w}; *(u32x2*)(lds + BUF + voffl) = a; *(u32x2*)(lds + BUF + voffl + 8) = b; }
.LBB0_103:
	s_or_b64 exec, exec, s[18:19]
	s_movk_i32 s2, 0x88
	s_waitcnt vmcnt(0) lgkmcnt(0)
	v_mul_lo_u32 v34, v45, s2
	v_lshl_add_u32 v218, v46, 4, v34
	s_add_u32 s18, s56, 0x3000
	v_add_u32_e32 v34, 0, v218
	s_addc_u32 s19, s57, 0
	v_add_u32_e32 v35, 0x3400, v34
	v_lshl_add_u64 v[36:37], v[194:195], 1, s[18:19]
	ds_write2_b64 v35, v[38:39], v[40:41] offset1:1
	global_load_dwordx4 v[122:125], v[36:37], off
	v_lshl_add_u64 v[36:37], v[190:191], 1, s[18:19]
	global_load_dwordx4 v[126:129], v[36:37], off
	global_load_dwordx4 v[130:133], v[192:193], off offset:128
	s_and_saveexec_b64 s[18:19], s[44:45]
	s_cbranch_execz .LBB0_105
	s_waitcnt vmcnt(0) lgkmcnt(0)
	ds_write_b128 v43, v[122:125] offset:22016

; template <int DQK, bool STATIC>
; DI void attn_item8(const bf16_t* __restrict__ Q, const bf16_t* __restrict__ Kp, const bf16_t* __restrict__ Vt, int nkeys, char* lds,
;                   const bf16_t* __restrict__ Pg, bf16_t* __restrict__ Yg  , float mfix) {
;     ...
;     if (more) {
; #pragma unroll
;       for (int i = 0; i < NKC; ++i) rk[i] = *(const u32x4*)(Kp + (size_t)(j + 1) * 64 * DQK + koffg[i]);
; #pragma unroll
;       for (int i = 0; i < 1; ++i) rv[i] = *(const u32x4*)(vg + (size_t)i * 32 * T + (j + 1) * 64);
;     }
.LBB0_112:
	v_cndmask_b32_e64 v66, 0, 1, s[50:51]
	v_cmp_ne_u32_e64 s[48:49], 1, v66
	s_andn2_b64 vcc, exec, s[50:51]
	s_cbranch_vccnz .LBB0_114
	s_or_b32 s19, s18, s20
	s_add_i32 s35, s19, 2
	s_mul_hi_u32 s53, s35, 0x3000
	s_mulk_i32 s35, 0x3000
	s_add_u32 s52, s56, s35
	s_addc_u32 s53, s57, s53
	v_lshl_add_u64 v[66:67], v[194:195], 1, s[52:53]
	v_lshl_add_u64 v[68:69], v[190:191], 1, s[52:53]
	s_lshl_b32 s52, s19, 6
	s_ashr_i32 s53, s52, 31
	s_waitcnt vmcnt(0)
	global_load_dwordx4 v[122:125], v[66:67], off
	global_load_dwordx4 v[126:129], v[68:69], off
	v_lshl_add_u64 v[66:67], s[52:53], 1, v[192:193]
	global_load_dwordx4 v[130:133], v[66:67], off offset:256

; __global__ void __launch_bounds__(NTHR, 2) fwd_megakernel(Params p_byval) {
;   KP p = (KP)__builtin_amdgcn_kernarg_segment_ptr();
;   extern __shared__ __attribute__((aligned(16))) char lds[];
	.amdhsa_kernel _Z14fwd_megakernel6Params
		.amdhsa_group_segment_fixed_size 0
		.amdhsa_private_segment_fixed_size 0
		.amdhsa_kernarg_size 456
		.amdhsa_user_sgpr_count 2
		.amdhsa_user_sgpr_dispatch_ptr 0
		.amdhsa_user_sgpr_queue_ptr 0
		.amdhsa_user_sgpr_kernarg_segment_ptr 1
		.amdhsa_user_sgpr_dispatch_id 0
		.amdhsa_user_sgpr_kernarg_preload_length 0
		.amdhsa_user_sgpr_kernarg_preload_offset 0
		.amdhsa_user_sgpr_private_segment_size 0
		.amdhsa_uses_dynamic_stack 0
		.amdhsa_enable_private_segment 0
		.amdhsa_system_sgpr_workgroup_id_x 1
		.amdhsa_system_sgpr_workgroup_id_y 0
		.amdhsa_system_sgpr_workgroup_id_z 0
		.amdhsa_system_sgpr_workgroup_info 0
		.amdhsa_system_vgpr_workitem_id 2
		.amdhsa_next_free_vgpr 256
		.amdhsa_next_free_sgpr 102
		.amdhsa_accum_offset 256
		.amdhsa_reserve_vcc 1
		.amdhsa_float_round_mode_32 0
		.amdhsa_float_round_mode_16_64 0
		.amdhsa_float_denorm_mode_32 3
		.amdhsa_float_denorm_mode_16_64 3
		.amdhsa_dx10_clamp 1
		.amdhsa_ieee_mode 1
		.amdhsa_fp16_overflow 0
		.amdhsa_tg_split 0
		.amdhsa_exception_fp_ieee_invalid_op 0
		.amdhsa_exception_fp_denorm_src 0
		.amdhsa_exception_fp_ieee_div_zero 0
		.amdhsa_exception_fp_ieee_overflow 0
		.amdhsa_exception_fp_ieee_underflow 0
		.amdhsa_exception_fp_ieee_inexact 0
		.amdhsa_exception_int_div_zero 0
	.end_amdhsa_kernel

; __global__ void __launch_bounds__(NTHR, 2) fwd_megakernel(Params p_byval) {
amdhsa.kernels:
  - .agpr_count:     0
    .args:
      - .offset:         0
        .size:           200
        .value_kind:     by_value
      - .offset:         200
        .size:           4
        .value_kind:     hidden_block_count_x
      - .offset:         204
        .size:           4
        .value_kind:     hidden_block_count_y
      - .offset:         208
        .size:           4
        .value_kind:     hidden_block_count_z
      - .offset:         212
        .size:           2
        .value_kind:     hidden_group_size_x
      - .offset:         214
        .size:           2
        .value_kind:     hidden_group_size_y
      - .offset:         216
        .size:           2
        .value_kind:     hidden_group_size_z
      - .offset:         218
        .size:           2
        .value_kind:     hidden_remainder_x
      - .offset:         220
        .size:           2
        .value_kind:     hidden_remainder_y
      - .offset:         222
        .size:           2
        .value_kind:     hidden_remainder_z
      - .offset:         240
        .size:           8
        .value_kind:     hidden_global_offset_x
      - .offset:         248
        .size:           8
        .value_kind:     hidden_global_offset_y
      - .offset:         256
        .size:           8
        .value_kind:     hidden_global_offset_z
      - .offset:         264
        .size:           2
        .value_kind:     hidden_grid_dims
      - .offset:         288
        .size:           8
        .value_kind:     hidden_multigrid_sync_arg
      - .offset:         320
        .size:           4
        .value_kind:     hidden_dynamic_lds_size
    .group_segment_fixed_size: 0
    .kernarg_segment_align: 8
    .kernarg_segment_size: 456
    .language:       OpenCL C
    .language_version:
      - 2
      - 0
    .max_flat_workgroup_size: 512
    .name:           _Z14fwd_megakernel6Params
    .private_segment_fixed_size: 0
    .sgpr_count:     108
    .sgpr_spill_count: 224
    .symbol:         _Z14fwd_megakernel6Params.kd
    .uniform_work_group_size: 1
    .uses_dynamic_stack: false
    .vgpr_count:     256
    .vgpr_spill_count: 0
    .wavefront_size: 64
